# v23 + P5 fused epilogue: all residual loads hoisted above the write-through stores, vmcnt re-derived
# speedup vs baseline: 1.0073x; 1.0073x over previous
.LBB0_688:
	s_lshl_b32 s4, s31, 5
	s_lshl_b32 s5, s28, 8
	s_or_b32 s4, s5, s4
	s_lshl_b32 s22, s30, 8
	v_and_or_b32 v146, v187, 24, s4
	s_add_i32 s4, s22, s29
	v_or_b32_e32 v150, s4, v189
	v_ashrrev_i32_e32 v151, 31, v150
	v_ashrrev_i32_e32 v147, 31, v146
	v_lshlrev_b64 v[164:165], 11, v[150:151]
	v_lshl_add_u64 v[130:131], s[8:9], 0, v[164:165]
	v_lshlrev_b64 v[148:149], 1, v[146:147]
	v_lshl_add_u64 v[130:131], v[130:131], 0, v[148:149]
	s_barrier
	s_mov_b64 s[98:99], 0x8000
	s_mov_b64 s[100:101], 0x28000
	v_mov_b64_e32 v[176:177], v[130:131]
	global_load_dwordx4 v[192:195], v[176:177], off
	global_load_dwordx4 v[196:199], v[176:177], off offset:256
	v_lshl_add_u64 v[176:177], v[176:177], 0, s[98:99]
	global_load_dwordx4 v[200:203], v[176:177], off
	global_load_dwordx4 v[204:207], v[176:177], off offset:256
	v_lshl_add_u64 v[176:177], v[176:177], 0, s[98:99]
	global_load_dwordx4 v[208:211], v[176:177], off
	global_load_dwordx4 v[212:215], v[176:177], off offset:256
	v_lshl_add_u64 v[176:177], v[176:177], 0, s[98:99]
	global_load_dwordx4 v[216:219], v[176:177], off
	global_load_dwordx4 v[220:223], v[176:177], off offset:256
	v_lshl_add_u64 v[176:177], v[176:177], 0, s[100:101]
	global_load_dwordx4 v[224:227], v[176:177], off
	global_load_dwordx4 v[228:231], v[176:177], off offset:256
	v_lshl_add_u64 v[176:177], v[176:177], 0, s[98:99]
	global_load_dwordx4 v[232:235], v[176:177], off
	global_load_dwordx4 v[236:239], v[176:177], off offset:256
	v_lshl_add_u64 v[176:177], v[176:177], 0, s[98:99]
	global_load_dwordx4 v[240:243], v[176:177], off
	global_load_dwordx4 v[244:247], v[176:177], off offset:256
	v_lshl_add_u64 v[176:177], v[176:177], 0, s[98:99]
	global_load_dwordx4 v[178:181], v[176:177], off
	global_load_dwordx4 v[182:185], v[176:177], off offset:256
	v_add_u32_e32 v151, s22, v154
	v_or_b32_e32 v130, 32, v151
	v_or_b32_e32 v132, 16, v150
	v_ashrrev_i32_e32 v131, 31, v130
	v_ashrrev_i32_e32 v133, 31, v132
	v_lshlrev_b64 v[130:131], 11, v[130:131]
	v_lshlrev_b64 v[152:153], 11, v[132:133]
	v_lshl_add_u64 v[130:131], s[8:9], 0, v[130:131]
	v_lshl_add_u64 v[132:133], s[8:9], 0, v[152:153]
	v_lshl_add_u64 v[130:131], v[130:131], 0, v[148:149]
	v_lshl_add_u64 v[138:139], v[132:133], 0, v[148:149]
	s_nop 0
	s_nop 0
	s_nop 0
	v_lshl_add_u64 v[164:165], s[18:19], 0, v[164:165]
	s_mov_b64 s[4:5], 0x100
	v_lshl_add_u64 v[164:165], v[164:165], 0, v[148:149]
	v_lshl_add_u64 v[166:167], v[164:165], 0, s[4:5]
	s_lshl_b32 s6, s31, 2
	s_add_i32 s23, s6, 0
	v_cmp_gt_u32_e32 vcc, 16, v190
	s_waitcnt vmcnt(15)
	v_lshlrev_b32_e32 v168, 16, v192
	v_and_b32_e32 v169, 0xffff0000, v192
	v_lshlrev_b32_e32 v156, 16, v193
	v_and_b32_e32 v157, 0xffff0000, v193
	v_lshlrev_b32_e32 v170, 16, v194
	v_and_b32_e32 v171, 0xffff0000, v194
	v_lshlrev_b32_e32 v158, 16, v195
	v_and_b32_e32 v159, 0xffff0000, v195
	s_waitcnt vmcnt(14)
	v_lshlrev_b32_e32 v172, 16, v196
	v_and_b32_e32 v173, 0xffff0000, v196
	v_lshlrev_b32_e32 v160, 16, v197
	v_and_b32_e32 v161, 0xffff0000, v197
	v_lshlrev_b32_e32 v174, 16, v198
	v_and_b32_e32 v175, 0xffff0000, v198
	v_lshlrev_b32_e32 v162, 16, v199
	v_and_b32_e32 v163, 0xffff0000, v199
	v_pk_add_f32 v[128:129], v[128:129], v[156:157]
	v_pk_add_f32 v[126:127], v[126:127], v[168:169]
	v_pk_add_f32 v[124:125], v[124:125], v[158:159]
	v_pk_add_f32 v[122:123], v[122:123], v[170:171]
	v_pk_add_f32 v[120:121], v[120:121], v[160:161]
	v_pk_add_f32 v[118:119], v[118:119], v[172:173]
	v_pk_add_f32 v[156:157], v[116:117], v[162:163]
	v_pk_add_f32 v[158:159], v[114:115], v[174:175]
	v_cvt_pk_bf16_f32 v114, v126, v127
	v_cvt_pk_bf16_f32 v115, v128, v129
	v_cvt_pk_bf16_f32 v116, v122, v123
	v_cvt_pk_bf16_f32 v117, v124, v125
	v_mul_f32_e32 v127, v127, v127
	v_mul_f32_e32 v129, v129, v129
	v_mul_f32_e32 v123, v123, v123
	v_mul_f32_e32 v125, v125, v125
	v_mul_f32_e32 v155, v119, v119
	v_mul_f32_e32 v160, v121, v121
	v_mul_f32_e32 v161, v159, v159
	v_mul_f32_e32 v162, v157, v157
	global_store_dwordx4 v[164:165], v[114:117], off sc1
	s_nop 1
	v_fmac_f32_e32 v127, v126, v126
	v_fmac_f32_e32 v129, v128, v128
	v_fmac_f32_e32 v123, v122, v122
	v_fmac_f32_e32 v125, v124, v124
	v_cvt_pk_bf16_f32 v114, v118, v119
	v_cvt_pk_bf16_f32 v115, v120, v121
	v_cvt_pk_bf16_f32 v116, v158, v159
	v_fmac_f32_e32 v155, v118, v118
	v_fmac_f32_e32 v160, v120, v120
	v_fmac_f32_e32 v161, v158, v158
	v_fmac_f32_e32 v162, v156, v156
	v_cvt_pk_bf16_f32 v117, v156, v157
	v_add_f32_e32 v118, v127, v129
	v_add_f32_e32 v119, v123, v125
	global_store_dwordx4 v[166:167], v[114:117], off sc1
	s_nop 1
	v_add_f32_e32 v114, v155, v160
	v_add_f32_e32 v116, v161, v162
	v_add_f32_e32 v115, v118, v119
	v_add_f32_e32 v114, v114, v116
	v_add_f32_e32 v114, v115, v114
	v_mov_b32_e32 v115, v114
	s_nop 1
	v_permlane16_swap_b32_e32 v114, v115
	v_add_f32_e32 v114, v114, v115
	v_mov_b32_e32 v115, v114
	s_nop 1
	v_permlane32_swap_b32_e32 v114, v115
	v_lshl_add_u32 v122, v154, 4, s23
	s_and_saveexec_b64 s[6:7], vcc
	v_add_f32_e32 v114, v114, v115
	ds_write_b32 v122, v114
	s_or_b64 exec, exec, s[6:7]
	v_or_b32_e32 v114, 48, v151
	v_ashrrev_i32_e32 v115, 31, v114
	v_lshlrev_b64 v[114:115], 11, v[114:115]
	v_lshl_add_u64 v[114:115], s[8:9], 0, v[114:115]
	v_lshl_add_u64 v[114:115], v[114:115], 0, v[148:149]
	s_nop 0
	s_waitcnt vmcnt(15)
	v_lshlrev_b32_e32 v126, 16, v201
	v_and_b32_e32 v127, 0xffff0000, v201
	s_waitcnt vmcnt(14)
	v_lshlrev_b32_e32 v154, 16, v206
	v_and_b32_e32 v155, 0xffff0000, v206
	v_lshlrev_b32_e32 v124, 16, v200
	v_and_b32_e32 v125, 0xffff0000, v200
	v_lshlrev_b32_e32 v128, 16, v202
	v_and_b32_e32 v129, 0xffff0000, v202
	v_pk_add_f32 v[112:113], v[112:113], v[126:127]
	v_pk_add_f32 v[126:127], v[98:99], v[154:155]
	v_lshl_add_u64 v[98:99], s[18:19], 0, v[152:153]
	v_lshlrev_b32_e32 v142, 16, v203
	v_and_b32_e32 v143, 0xffff0000, v203
	v_lshlrev_b32_e32 v140, 16, v207
	v_and_b32_e32 v141, 0xffff0000, v207
	v_pk_add_f32 v[110:111], v[110:111], v[124:125]
	v_pk_add_f32 v[106:107], v[106:107], v[128:129]
	v_lshl_add_u64 v[128:129], v[98:99], 0, v[148:149]
	v_cvt_pk_bf16_f32 v98, v110, v111
	v_cvt_pk_bf16_f32 v99, v112, v113
	v_pk_add_f32 v[108:109], v[108:109], v[142:143]
	v_pk_add_f32 v[124:125], v[100:101], v[140:141]
	v_cvt_pk_bf16_f32 v100, v106, v107
	v_cvt_pk_bf16_f32 v101, v108, v109
	v_lshlrev_b32_e32 v144, 16, v204
	global_store_dwordx4 v[128:129], v[98:101], off sc1
	s_nop 1
	v_mul_f32_e32 v98, v111, v111
	v_mul_f32_e32 v99, v113, v113
	v_fmac_f32_e32 v98, v110, v110
	v_fmac_f32_e32 v99, v112, v112
	v_add_f32_e32 v98, v98, v99
	v_mul_f32_e32 v99, v107, v107
	v_mul_f32_e32 v100, v109, v109
	v_fmac_f32_e32 v99, v106, v106
	v_fmac_f32_e32 v100, v108, v108
	v_and_b32_e32 v145, 0xffff0000, v204
	v_lshlrev_b32_e32 v138, 16, v205
	v_and_b32_e32 v139, 0xffff0000, v205
	v_add_f32_e32 v99, v99, v100
	v_pk_add_f32 v[104:105], v[104:105], v[138:139]
	v_pk_add_f32 v[102:103], v[102:103], v[144:145]
	v_add_f32_e32 v108, v98, v99
	v_cvt_pk_bf16_f32 v98, v102, v103
	v_cvt_pk_bf16_f32 v99, v104, v105
	v_lshl_add_u64 v[106:107], v[128:129], 0, s[4:5]
	v_cvt_pk_bf16_f32 v100, v126, v127
	v_cvt_pk_bf16_f32 v101, v124, v125
	s_nop 0
	global_store_dwordx4 v[106:107], v[98:101], off sc1
	s_nop 1
	v_mul_f32_e32 v98, v103, v103
	v_mul_f32_e32 v99, v105, v105
	v_fmac_f32_e32 v98, v102, v102
	v_fmac_f32_e32 v99, v104, v104
	v_add_f32_e32 v98, v98, v99
	v_mul_f32_e32 v99, v127, v127
	v_mul_f32_e32 v100, v125, v125
	v_fmac_f32_e32 v99, v126, v126
	v_fmac_f32_e32 v100, v124, v124
	v_add_f32_e32 v99, v99, v100
	v_add_f32_e32 v98, v98, v99
	v_add_f32_e32 v98, v108, v98
	v_mov_b32_e32 v99, v98
	s_nop 1
	v_permlane16_swap_b32_e32 v98, v99
	v_add_f32_e32 v98, v98, v99
	v_mov_b32_e32 v99, v98
	s_nop 1
	v_permlane32_swap_b32_e32 v98, v99
	s_and_saveexec_b64 s[4:5], vcc
	v_add_f32_e32 v98, v98, v99
	ds_write_b32 v122, v98 offset:256
	s_or_b64 exec, exec, s[4:5]
	v_add_u32_e32 v98, 0x80, v151
	v_ashrrev_i32_e32 v99, 31, v98
	v_lshlrev_b64 v[98:99], 11, v[98:99]
	v_lshl_add_u64 v[98:99], s[8:9], 0, v[98:99]
	v_lshl_add_u64 v[98:99], v[98:99], 0, v[148:149]
	s_nop 0
	s_waitcnt vmcnt(15)
	v_lshlrev_b32_e32 v108, 16, v209
	v_and_b32_e32 v109, 0xffff0000, v209
	s_waitcnt vmcnt(14)
	v_lshlrev_b32_e32 v128, 16, v214
	v_and_b32_e32 v129, 0xffff0000, v214
	v_pk_add_f32 v[96:97], v[96:97], v[108:109]
	v_pk_add_f32 v[108:109], v[82:83], v[128:129]
	v_or_b32_e32 v82, 32, v150
	v_ashrrev_i32_e32 v83, 31, v82
	v_lshlrev_b64 v[82:83], 11, v[82:83]
	v_lshlrev_b32_e32 v106, 16, v208
	v_and_b32_e32 v107, 0xffff0000, v208
	v_lshlrev_b32_e32 v110, 16, v210
	v_and_b32_e32 v111, 0xffff0000, v210
	v_lshl_add_u64 v[82:83], s[18:19], 0, v[82:83]
	v_lshlrev_b32_e32 v112, 16, v211
	v_and_b32_e32 v113, 0xffff0000, v211
	v_lshlrev_b32_e32 v124, 16, v212
	v_and_b32_e32 v125, 0xffff0000, v212
	v_lshlrev_b32_e32 v126, 16, v213
	v_and_b32_e32 v127, 0xffff0000, v213
	v_lshlrev_b32_e32 v130, 16, v215
	v_and_b32_e32 v131, 0xffff0000, v215
	v_pk_add_f32 v[94:95], v[94:95], v[106:107]
	v_pk_add_f32 v[90:91], v[90:91], v[110:111]
	v_lshl_add_u64 v[110:111], v[82:83], 0, v[148:149]
	v_cvt_pk_bf16_f32 v82, v94, v95
	v_cvt_pk_bf16_f32 v83, v96, v97
	v_pk_add_f32 v[92:93], v[92:93], v[112:113]
	v_pk_add_f32 v[106:107], v[84:85], v[130:131]
	v_cvt_pk_bf16_f32 v84, v90, v91
	v_cvt_pk_bf16_f32 v85, v92, v93
	v_pk_add_f32 v[88:89], v[88:89], v[126:127]
	global_store_dwordx4 v[110:111], v[82:85], off sc1
	s_nop 1
	v_mul_f32_e32 v82, v95, v95
	v_mul_f32_e32 v83, v97, v97
	v_fmac_f32_e32 v82, v94, v94
	v_fmac_f32_e32 v83, v96, v96
	v_add_f32_e32 v82, v82, v83
	v_mul_f32_e32 v83, v91, v91
	v_mul_f32_e32 v84, v93, v93
	v_fmac_f32_e32 v83, v90, v90
	v_fmac_f32_e32 v84, v92, v92
	v_add_f32_e32 v83, v83, v84
	v_pk_add_f32 v[86:87], v[86:87], v[124:125]
	v_add_f32_e32 v92, v82, v83
	s_mov_b64 s[4:5], 0x100
	v_cvt_pk_bf16_f32 v82, v86, v87
	v_cvt_pk_bf16_f32 v83, v88, v89
	v_lshl_add_u64 v[90:91], v[110:111], 0, s[4:5]
	v_cvt_pk_bf16_f32 v84, v108, v109
	v_cvt_pk_bf16_f32 v85, v106, v107
	s_nop 0
	global_store_dwordx4 v[90:91], v[82:85], off sc1
	s_nop 1
	v_mul_f32_e32 v82, v87, v87
	v_mul_f32_e32 v83, v89, v89
	v_fmac_f32_e32 v82, v86, v86
	v_fmac_f32_e32 v83, v88, v88
	v_add_f32_e32 v82, v82, v83
	v_mul_f32_e32 v83, v109, v109
	v_mul_f32_e32 v84, v107, v107
	v_fmac_f32_e32 v83, v108, v108
	v_fmac_f32_e32 v84, v106, v106
	v_add_f32_e32 v83, v83, v84
	v_add_f32_e32 v82, v82, v83
	v_add_f32_e32 v82, v92, v82
	v_mov_b32_e32 v83, v82
	s_nop 1
	v_permlane16_swap_b32_e32 v82, v83
	v_add_f32_e32 v82, v82, v83
	v_mov_b32_e32 v83, v82
	s_nop 1
	v_permlane32_swap_b32_e32 v82, v83
	s_and_saveexec_b64 s[6:7], vcc
	v_add_f32_e32 v82, v82, v83
	ds_write_b32 v122, v82 offset:512
	s_or_b64 exec, exec, s[6:7]
	v_add_u32_e32 v82, 0x90, v151
	v_ashrrev_i32_e32 v83, 31, v82
	v_lshlrev_b64 v[82:83], 11, v[82:83]
	v_lshl_add_u64 v[82:83], s[8:9], 0, v[82:83]
	v_lshl_add_u64 v[82:83], v[82:83], 0, v[148:149]
	s_nop 0
	s_waitcnt vmcnt(15)
	v_lshlrev_b32_e32 v92, 16, v217
	v_and_b32_e32 v93, 0xffff0000, v217
	s_waitcnt vmcnt(14)
	v_lshlrev_b32_e32 v110, 16, v222
	v_and_b32_e32 v111, 0xffff0000, v222
	v_pk_add_f32 v[80:81], v[80:81], v[92:93]
	v_pk_add_f32 v[92:93], v[66:67], v[110:111]
	v_or_b32_e32 v66, 48, v150
	v_ashrrev_i32_e32 v67, 31, v66
	v_lshlrev_b64 v[66:67], 11, v[66:67]
	v_lshlrev_b32_e32 v90, 16, v216
	v_and_b32_e32 v91, 0xffff0000, v216
	v_lshlrev_b32_e32 v94, 16, v218
	v_and_b32_e32 v95, 0xffff0000, v218
	v_lshl_add_u64 v[66:67], s[18:19], 0, v[66:67]
	v_lshlrev_b32_e32 v96, 16, v219
	v_and_b32_e32 v97, 0xffff0000, v219
	v_lshlrev_b32_e32 v112, 16, v223
	v_and_b32_e32 v113, 0xffff0000, v223
	v_pk_add_f32 v[78:79], v[78:79], v[90:91]
	v_pk_add_f32 v[74:75], v[74:75], v[94:95]
	v_lshl_add_u64 v[94:95], v[66:67], 0, v[148:149]
	v_cvt_pk_bf16_f32 v66, v78, v79
	v_cvt_pk_bf16_f32 v67, v80, v81
	v_pk_add_f32 v[76:77], v[76:77], v[96:97]
	v_pk_add_f32 v[90:91], v[68:69], v[112:113]
	v_cvt_pk_bf16_f32 v68, v74, v75
	v_cvt_pk_bf16_f32 v69, v76, v77
	v_lshlrev_b32_e32 v106, 16, v220
	global_store_dwordx4 v[94:95], v[66:69], off sc1
	s_nop 1
	v_mul_f32_e32 v66, v79, v79
	v_mul_f32_e32 v67, v81, v81
	v_fmac_f32_e32 v66, v78, v78
	v_fmac_f32_e32 v67, v80, v80
	v_add_f32_e32 v66, v66, v67
	v_mul_f32_e32 v67, v75, v75
	v_mul_f32_e32 v68, v77, v77
	v_fmac_f32_e32 v67, v74, v74
	v_fmac_f32_e32 v68, v76, v76
	v_and_b32_e32 v107, 0xffff0000, v220
	v_lshlrev_b32_e32 v108, 16, v221
	v_and_b32_e32 v109, 0xffff0000, v221
	v_add_f32_e32 v67, v67, v68
	v_pk_add_f32 v[72:73], v[72:73], v[108:109]
	v_pk_add_f32 v[70:71], v[70:71], v[106:107]
	v_add_f32_e32 v76, v66, v67
	v_cvt_pk_bf16_f32 v66, v70, v71
	v_cvt_pk_bf16_f32 v67, v72, v73
	v_lshl_add_u64 v[74:75], v[94:95], 0, s[4:5]
	v_cvt_pk_bf16_f32 v68, v92, v93
	v_cvt_pk_bf16_f32 v69, v90, v91
	s_nop 0
	global_store_dwordx4 v[74:75], v[66:69], off sc1
	s_nop 1
	v_mul_f32_e32 v66, v71, v71
	v_mul_f32_e32 v67, v73, v73
	v_fmac_f32_e32 v66, v70, v70
	v_fmac_f32_e32 v67, v72, v72
	v_add_f32_e32 v66, v66, v67
	v_mul_f32_e32 v67, v93, v93
	v_mul_f32_e32 v68, v91, v91
	v_fmac_f32_e32 v67, v92, v92
	v_fmac_f32_e32 v68, v90, v90
	v_add_f32_e32 v67, v67, v68
	v_add_f32_e32 v66, v66, v67
	v_add_f32_e32 v66, v76, v66
	v_mov_b32_e32 v67, v66
	s_nop 1
	v_permlane16_swap_b32_e32 v66, v67
	v_add_f32_e32 v66, v66, v67
	v_mov_b32_e32 v67, v66
	s_nop 1
	v_permlane32_swap_b32_e32 v66, v67
	s_and_saveexec_b64 s[4:5], vcc
	v_add_f32_e32 v66, v66, v67
	ds_write_b32 v122, v66 offset:768
	s_or_b64 exec, exec, s[4:5]
	v_add_u32_e32 v66, 0xa0, v151
	v_ashrrev_i32_e32 v67, 31, v66
	v_lshlrev_b64 v[66:67], 11, v[66:67]
	v_lshl_add_u64 v[66:67], s[8:9], 0, v[66:67]
	v_lshl_add_u64 v[66:67], v[66:67], 0, v[148:149]
	s_nop 0
	s_waitcnt vmcnt(15)
	v_lshlrev_b32_e32 v74, 16, v224
	v_and_b32_e32 v75, 0xffff0000, v224
	v_lshlrev_b32_e32 v78, 16, v226
	v_and_b32_e32 v79, 0xffff0000, v226
	v_pk_add_f32 v[62:63], v[62:63], v[74:75]
	v_pk_add_f32 v[74:75], v[58:59], v[78:79]
	v_add_u32_e32 v58, 0x80, v150
	s_waitcnt vmcnt(14)
	v_lshlrev_b32_e32 v94, 16, v230
	v_and_b32_e32 v95, 0xffff0000, v230
	v_ashrrev_i32_e32 v59, 31, v58
	v_pk_add_f32 v[78:79], v[50:51], v[94:95]
	v_lshlrev_b64 v[50:51], 11, v[58:59]
	v_lshlrev_b32_e32 v76, 16, v225
	v_and_b32_e32 v77, 0xffff0000, v225
	v_lshlrev_b32_e32 v80, 16, v227
	v_and_b32_e32 v81, 0xffff0000, v227
	v_lshl_add_u64 v[50:51], s[18:19], 0, v[50:51]
	v_lshlrev_b32_e32 v96, 16, v231
	v_and_b32_e32 v97, 0xffff0000, v231
	v_pk_add_f32 v[64:65], v[64:65], v[76:77]
	v_pk_add_f32 v[60:61], v[60:61], v[80:81]
	v_lshl_add_u64 v[80:81], v[50:51], 0, v[148:149]
	v_cvt_pk_bf16_f32 v50, v62, v63
	v_cvt_pk_bf16_f32 v51, v64, v65
	v_pk_add_f32 v[76:77], v[52:53], v[96:97]
	v_cvt_pk_bf16_f32 v52, v74, v75
	v_cvt_pk_bf16_f32 v53, v60, v61
	v_lshlrev_b32_e32 v90, 16, v228
	global_store_dwordx4 v[80:81], v[50:53], off sc1
	s_nop 1
	v_mul_f32_e32 v50, v63, v63
	v_mul_f32_e32 v51, v65, v65
	v_fmac_f32_e32 v50, v62, v62
	v_fmac_f32_e32 v51, v64, v64
	v_add_f32_e32 v50, v50, v51
	v_mul_f32_e32 v51, v75, v75
	v_mul_f32_e32 v52, v61, v61
	v_fmac_f32_e32 v51, v74, v74
	v_fmac_f32_e32 v52, v60, v60
	v_and_b32_e32 v91, 0xffff0000, v228
	v_lshlrev_b32_e32 v92, 16, v229
	v_and_b32_e32 v93, 0xffff0000, v229
	v_add_f32_e32 v51, v51, v52
	v_pk_add_f32 v[56:57], v[56:57], v[92:93]
	v_pk_add_f32 v[54:55], v[54:55], v[90:91]
	v_add_f32_e32 v59, v50, v51
	s_mov_b64 s[4:5], 0x100
	v_cvt_pk_bf16_f32 v50, v54, v55
	v_cvt_pk_bf16_f32 v51, v56, v57
	v_lshl_add_u64 v[60:61], v[80:81], 0, s[4:5]
	v_cvt_pk_bf16_f32 v52, v78, v79
	v_cvt_pk_bf16_f32 v53, v76, v77
	s_addk_i32 s29, 0x80
	global_store_dwordx4 v[60:61], v[50:53], off sc1
	s_nop 1
	v_mul_f32_e32 v50, v55, v55
	v_mul_f32_e32 v51, v57, v57
	v_fmac_f32_e32 v50, v54, v54
	v_fmac_f32_e32 v51, v56, v56
	v_add_f32_e32 v50, v50, v51
	v_mul_f32_e32 v51, v79, v79
	v_mul_f32_e32 v52, v77, v77
	v_fmac_f32_e32 v51, v78, v78
	v_fmac_f32_e32 v52, v76, v76
	v_add_f32_e32 v51, v51, v52
	v_add_f32_e32 v50, v50, v51
	v_add_f32_e32 v50, v59, v50
	v_mov_b32_e32 v51, v50
	s_nop 1
	v_permlane16_swap_b32_e32 v50, v51
	v_add_f32_e32 v50, v50, v51
	v_mov_b32_e32 v51, v50
	v_or_b32_e32 v52, s29, v189
	s_nop 0
	v_permlane32_swap_b32_e32 v50, v51
	v_lshl_add_u32 v59, v52, 4, s23
	s_and_saveexec_b64 s[6:7], vcc
	v_add_f32_e32 v50, v50, v51
	ds_write_b32 v59, v50
	s_or_b64 exec, exec, s[6:7]
	v_add_u32_e32 v50, 0xb0, v151
	v_ashrrev_i32_e32 v51, 31, v50
	v_lshlrev_b64 v[50:51], 11, v[50:51]
	v_lshl_add_u64 v[50:51], s[8:9], 0, v[50:51]
	v_lshl_add_u64 v[50:51], v[50:51], 0, v[148:149]
	s_nop 0
	s_waitcnt vmcnt(15)
	v_lshlrev_b32_e32 v62, 16, v233
	v_and_b32_e32 v63, 0xffff0000, v233
	s_waitcnt vmcnt(14)
	v_lshlrev_b32_e32 v80, 16, v238
	v_and_b32_e32 v81, 0xffff0000, v238
	v_pk_add_f32 v[48:49], v[48:49], v[62:63]
	v_pk_add_f32 v[62:63], v[34:35], v[80:81]
	v_or_b32_e32 v34, 16, v58
	v_ashrrev_i32_e32 v35, 31, v34
	v_lshlrev_b64 v[34:35], 11, v[34:35]
	v_lshlrev_b32_e32 v60, 16, v232
	v_and_b32_e32 v61, 0xffff0000, v232
	v_lshlrev_b32_e32 v64, 16, v234
	v_and_b32_e32 v65, 0xffff0000, v234
	v_lshl_add_u64 v[34:35], s[18:19], 0, v[34:35]
	v_lshlrev_b32_e32 v74, 16, v235
	v_and_b32_e32 v75, 0xffff0000, v235
	v_lshlrev_b32_e32 v76, 16, v236
	v_and_b32_e32 v77, 0xffff0000, v236
	v_lshlrev_b32_e32 v78, 16, v237
	v_and_b32_e32 v79, 0xffff0000, v237
	v_lshlrev_b32_e32 v82, 16, v239
	v_and_b32_e32 v83, 0xffff0000, v239
	v_pk_add_f32 v[46:47], v[46:47], v[60:61]
	v_pk_add_f32 v[42:43], v[42:43], v[64:65]
	v_lshl_add_u64 v[64:65], v[34:35], 0, v[148:149]
	v_cvt_pk_bf16_f32 v34, v46, v47
	v_cvt_pk_bf16_f32 v35, v48, v49
	v_pk_add_f32 v[44:45], v[44:45], v[74:75]
	v_pk_add_f32 v[60:61], v[36:37], v[82:83]
	v_cvt_pk_bf16_f32 v36, v42, v43
	v_cvt_pk_bf16_f32 v37, v44, v45
	v_pk_add_f32 v[40:41], v[40:41], v[78:79]
	global_store_dwordx4 v[64:65], v[34:37], off sc1
	s_nop 1
	v_mul_f32_e32 v34, v47, v47
	v_mul_f32_e32 v35, v49, v49
	v_fmac_f32_e32 v34, v46, v46
	v_fmac_f32_e32 v35, v48, v48
	v_add_f32_e32 v34, v34, v35
	v_mul_f32_e32 v35, v43, v43
	v_mul_f32_e32 v36, v45, v45
	v_fmac_f32_e32 v35, v42, v42
	v_fmac_f32_e32 v36, v44, v44
	v_add_f32_e32 v35, v35, v36
	v_pk_add_f32 v[38:39], v[38:39], v[76:77]
	v_add_f32_e32 v44, v34, v35
	v_cvt_pk_bf16_f32 v34, v38, v39
	v_cvt_pk_bf16_f32 v35, v40, v41
	v_lshl_add_u64 v[42:43], v[64:65], 0, s[4:5]
	v_cvt_pk_bf16_f32 v36, v62, v63
	v_cvt_pk_bf16_f32 v37, v60, v61
	s_nop 0
	global_store_dwordx4 v[42:43], v[34:37], off sc1
	s_nop 1
	v_mul_f32_e32 v34, v39, v39
	v_mul_f32_e32 v35, v41, v41
	v_fmac_f32_e32 v34, v38, v38
	v_fmac_f32_e32 v35, v40, v40
	v_add_f32_e32 v34, v34, v35
	v_mul_f32_e32 v35, v63, v63
	v_mul_f32_e32 v36, v61, v61
	v_fmac_f32_e32 v35, v62, v62
	v_fmac_f32_e32 v36, v60, v60
	v_add_f32_e32 v35, v35, v36
	v_add_f32_e32 v34, v34, v35
	v_add_f32_e32 v34, v44, v34
	v_mov_b32_e32 v35, v34
	s_nop 1
	v_permlane16_swap_b32_e32 v34, v35
	v_add_f32_e32 v34, v34, v35
	v_mov_b32_e32 v35, v34
	s_nop 1
	v_permlane32_swap_b32_e32 v34, v35
	s_and_saveexec_b64 s[4:5], vcc
	v_add_f32_e32 v34, v34, v35
	ds_write_b32 v59, v34 offset:256
	s_or_b64 exec, exec, s[4:5]
	s_waitcnt vmcnt(14)
	v_lshlrev_b32_e32 v42, 16, v244
	v_and_b32_e32 v43, 0xffff0000, v244
	v_pk_add_f32 v[42:43], v[18:19], v[42:43]
	v_or_b32_e32 v18, 32, v58
	v_ashrrev_i32_e32 v19, 31, v18
	v_lshlrev_b64 v[18:19], 11, v[18:19]
	v_lshlrev_b32_e32 v34, 16, v240
	v_and_b32_e32 v35, 0xffff0000, v240
	v_lshlrev_b32_e32 v36, 16, v241
	v_and_b32_e32 v37, 0xffff0000, v241
	v_lshl_add_u64 v[18:19], s[18:19], 0, v[18:19]
	v_lshlrev_b32_e32 v38, 16, v242
	v_and_b32_e32 v39, 0xffff0000, v242
	v_lshlrev_b32_e32 v40, 16, v243
	v_and_b32_e32 v41, 0xffff0000, v243
	v_lshlrev_b32_e32 v44, 16, v245
	v_and_b32_e32 v45, 0xffff0000, v245
	v_pk_add_f32 v[26:27], v[26:27], v[34:35]
	v_pk_add_f32 v[28:29], v[28:29], v[36:37]
	v_lshl_add_u64 v[34:35], v[146:147], 1, v[18:19]
	v_cvt_pk_bf16_f32 v18, v26, v27
	v_cvt_pk_bf16_f32 v19, v28, v29
	v_pk_add_f32 v[44:45], v[20:21], v[44:45]
	v_pk_add_f32 v[30:31], v[30:31], v[38:39]
	v_pk_add_f32 v[32:33], v[32:33], v[40:41]
	v_cvt_pk_bf16_f32 v20, v30, v31
	v_lshlrev_b32_e32 v46, 16, v246
	v_cvt_pk_bf16_f32 v21, v32, v33
	v_and_b32_e32 v47, 0xffff0000, v246
	global_store_dwordx4 v[34:35], v[18:21], off sc1
	s_nop 1
	v_mul_f32_e32 v18, v27, v27
	v_mul_f32_e32 v19, v29, v29
	v_fmac_f32_e32 v18, v26, v26
	v_fmac_f32_e32 v19, v28, v28
	v_add_f32_e32 v18, v18, v19
	v_mul_f32_e32 v19, v31, v31
	v_mul_f32_e32 v20, v33, v33
	v_fmac_f32_e32 v19, v30, v30
	v_fmac_f32_e32 v20, v32, v32
	v_add_f32_e32 v19, v19, v20
	v_lshlrev_b32_e32 v48, 16, v247
	v_and_b32_e32 v49, 0xffff0000, v247
	v_add_f32_e32 v28, v19, v18
	s_mov_b64 s[4:5], 0x100
	v_cvt_pk_bf16_f32 v18, v42, v43
	v_cvt_pk_bf16_f32 v19, v44, v45
	v_pk_add_f32 v[22:23], v[22:23], v[46:47]
	v_pk_add_f32 v[24:25], v[24:25], v[48:49]
	v_lshl_add_u64 v[26:27], v[34:35], 0, s[4:5]
	v_cvt_pk_bf16_f32 v20, v22, v23
	v_cvt_pk_bf16_f32 v21, v24, v25
	s_nop 0
	global_store_dwordx4 v[26:27], v[18:21], off sc1
	s_nop 1
	v_mul_f32_e32 v18, v43, v43
	v_mul_f32_e32 v19, v45, v45
	v_fmac_f32_e32 v18, v42, v42
	v_fmac_f32_e32 v19, v44, v44
	v_add_f32_e32 v18, v18, v19
	v_mul_f32_e32 v19, v23, v23
	v_mul_f32_e32 v20, v25, v25
	v_fmac_f32_e32 v19, v22, v22
	v_fmac_f32_e32 v20, v24, v24
	v_add_f32_e32 v19, v19, v20
	v_add_f32_e32 v18, v19, v18
	v_add_f32_e32 v18, v28, v18
	v_mov_b32_e32 v19, v18
	s_nop 1
	v_permlane16_swap_b32_e32 v18, v19
	v_add_f32_e32 v18, v18, v19
	v_mov_b32_e32 v19, v18
	s_nop 1
	v_permlane32_swap_b32_e32 v18, v19
	s_and_saveexec_b64 s[6:7], vcc
	v_add_f32_e32 v18, v18, v19
	ds_write_b32 v59, v18 offset:512
	s_or_b64 exec, exec, s[6:7]
	s_waitcnt vmcnt(14)
	v_lshlrev_b32_e32 v30, 16, v184
	v_and_b32_e32 v31, 0xffff0000, v184
	v_pk_add_f32 v[30:31], v[2:3], v[30:31]
	v_or_b32_e32 v2, 48, v58
	v_ashrrev_i32_e32 v3, 31, v2
	v_lshlrev_b64 v[2:3], 11, v[2:3]
	v_lshlrev_b32_e32 v18, 16, v178
	v_and_b32_e32 v19, 0xffff0000, v178
	v_lshlrev_b32_e32 v20, 16, v179
	v_and_b32_e32 v21, 0xffff0000, v179
	v_lshl_add_u64 v[2:3], s[18:19], 0, v[2:3]
	v_lshlrev_b32_e32 v22, 16, v180
	v_and_b32_e32 v23, 0xffff0000, v180
	v_lshlrev_b32_e32 v24, 16, v181
	v_and_b32_e32 v25, 0xffff0000, v181
	v_lshlrev_b32_e32 v32, 16, v185
	v_and_b32_e32 v33, 0xffff0000, v185
	v_pk_add_f32 v[10:11], v[10:11], v[18:19]
	v_pk_add_f32 v[12:13], v[12:13], v[20:21]
	v_lshl_add_u64 v[18:19], v[146:147], 1, v[2:3]
	v_cvt_pk_bf16_f32 v2, v10, v11
	v_cvt_pk_bf16_f32 v3, v12, v13
	v_pk_add_f32 v[32:33], v[4:5], v[32:33]
	v_pk_add_f32 v[14:15], v[14:15], v[22:23]
	v_pk_add_f32 v[16:17], v[16:17], v[24:25]
	v_cvt_pk_bf16_f32 v4, v14, v15
	v_lshlrev_b32_e32 v26, 16, v182
	v_cvt_pk_bf16_f32 v5, v16, v17
	v_and_b32_e32 v27, 0xffff0000, v182
	global_store_dwordx4 v[18:19], v[2:5], off sc1
	s_nop 1
	v_mul_f32_e32 v2, v11, v11
	v_mul_f32_e32 v3, v13, v13
	v_fmac_f32_e32 v2, v10, v10
	v_fmac_f32_e32 v3, v12, v12
	v_add_f32_e32 v2, v2, v3
	v_mul_f32_e32 v3, v15, v15
	v_mul_f32_e32 v4, v17, v17
	v_fmac_f32_e32 v3, v14, v14
	v_fmac_f32_e32 v4, v16, v16
	v_lshlrev_b32_e32 v28, 16, v183
	v_and_b32_e32 v29, 0xffff0000, v183
	v_add_f32_e32 v3, v3, v4
	v_pk_add_f32 v[6:7], v[6:7], v[26:27]
	v_pk_add_f32 v[8:9], v[8:9], v[28:29]
	v_add_f32_e32 v12, v3, v2
	v_cvt_pk_bf16_f32 v2, v6, v7
	v_cvt_pk_bf16_f32 v3, v8, v9
	v_lshl_add_u64 v[10:11], v[18:19], 0, s[4:5]
	v_cvt_pk_bf16_f32 v4, v30, v31
	v_cvt_pk_bf16_f32 v5, v32, v33
	s_nop 0
	global_store_dwordx4 v[10:11], v[2:5], off sc1
	s_nop 1
	v_mul_f32_e32 v2, v7, v7
	v_mul_f32_e32 v3, v9, v9
	v_fmac_f32_e32 v2, v6, v6
	v_fmac_f32_e32 v3, v8, v8
	v_add_f32_e32 v2, v2, v3
	v_mul_f32_e32 v3, v31, v31
	v_mul_f32_e32 v4, v33, v33
	v_fmac_f32_e32 v3, v30, v30
	v_fmac_f32_e32 v4, v32, v32
	v_add_f32_e32 v3, v3, v4
	v_add_f32_e32 v2, v3, v2
	v_add_f32_e32 v2, v12, v2
	v_mov_b32_e32 v3, v2
	s_nop 1
	v_permlane16_swap_b32_e32 v2, v3
	v_add_f32_e32 v2, v2, v3
	v_mov_b32_e32 v3, v2
	s_nop 1
	v_permlane32_swap_b32_e32 v2, v3
	s_and_saveexec_b64 s[4:5], vcc
	v_add_f32_e32 v2, v2, v3
	ds_write_b32 v59, v2 offset:768
	s_or_b64 exec, exec, s[4:5]
	s_waitcnt lgkmcnt(0)
	s_barrier
	s_andn2_b32 s1, s1, 63
	v_or_b32_e32 v2, s1, v190
	s_movk_i32 s1, 0x100
	v_cmp_gt_i32_e32 vcc, s1, v2
	s_and_saveexec_b64 s[4:5], vcc
	s_cbranch_execz .LBB0_706
	v_lshl_add_u32 v3, v2, 4, 0
	ds_read_b128 v[4:7], v3
	v_add_u32_e32 v2, s22, v2
	v_ashrrev_i32_e32 v3, 31, v2
	v_lshl_add_u64 v[2:3], v[2:3], 4, s[24:25]
	s_ashr_i32 s29, s28, 31
	s_waitcnt lgkmcnt(0)
	v_mov_b32_e32 v8, v5
	v_mov_b32_e32 v9, v6
	v_mov_b32_e32 v5, v7
	v_pk_add_f32 v[4:5], v[8:9], v[4:5]
	v_lshl_add_u64 v[2:3], s[28:29], 2, v[2:3]
	v_pk_add_f32 v[4:5], v[4:5], v[4:5] op_sel:[0,1] op_sel_hi:[1,0]
	global_store_dword v[2:3], v4, off sc1
